# phase 10: hand-written f32->fp8 expert table conversion with 4 rows per wave in flight (same arithmetic: IEEE 224/max division sequence, v_cvt_pk_fp8_f32)
# baseline (speedup 1.0000x reference)
; DEVI void conv_fp8_rows(const float* __restrict__ src, unsigned char* __restrict__ dst, float* __restrict__ inv_scale,
;                         int rows, int gw, int nw, int lane) {
;   for (int r0 = gw; r0 < rows; r0 += 2 * nw) {
;     const int r1 = r0 + nw;
;     const bool has1 = r1 < rows;
;     const float4* p0 = (const float4*)(src + (size_t)r0 * 1024) + lane * 4;
;     const float4* p1 = (const float4*)(src + (size_t)(has1 ? r1 : r0) * 1024) + lane * 4;
;     float4 v[2][4];
; #pragma unroll
;     for (int i = 0; i < 4; ++i) { v[0][i] = p0[i]; v[1][i] = p1[i]; }
;     float mx[2];
; #pragma unroll
;     for (int q = 0; q < 2; ++q) {
;       float m = 0.f;
; #pragma unroll
;       for (int i = 0; i < 4; ++i)
;         m = fmaxf(m, fmaxf(fmaxf(fabsf(v[q][i].x), fabsf(v[q][i].y)), fmaxf(fabsf(v[q][i].z), fabsf(v[q][i].w))));
;       mx[q] = m;
;     }
; #pragma unroll
;     for (int o = 32; o; o >>= 1) { mx[0] = fmaxf(mx[0], __shfl_xor(mx[0], o)); mx[1] = fmaxf(mx[1], __shfl_xor(mx[1], o)); }
; #pragma unroll
;     for (int q = 0; q < 2; ++q) {
;       if (q == 1 && !has1) break;
;       const int r = q ? r1 : r0;
;       const float sc = mx[q] > 0.f ? 224.f / mx[q] : 1.f;
;       if (lane == 0) inv_scale[r] = mx[q] > 0.f ? mx[q] * (1.f / 224.f) : 1.f;
;       uint4 o4;
;       o4.x = pk4_fp8(v[q][0].x * sc, v[q][0].y * sc, v[q][0].z * sc, v[q][0].w * sc);
;       o4.y = pk4_fp8(v[q][1].x * sc, v[q][1].y * sc, v[q][1].z * sc, v[q][1].w * sc);
;       o4.z = pk4_fp8(v[q][2].x * sc, v[q][2].y * sc, v[q][2].z * sc, v[q][2].w * sc);
;       o4.w = pk4_fp8(v[q][3].x * sc, v[q][3].y * sc, v[q][3].z * sc, v[q][3].w * sc);
;       ((uint4*)(dst + (size_t)r * 1024))[lane] = o4;
;     }
;   }
.LBB0_1223:
	s_waitcnt lgkmcnt(0)
	s_cmp_lg_u32 s33, 0x200
	s_cbranch_scc1 .Lp10_conv_compiler
	s_load_dwordx4 s[12:15], s[68:69], 0xc0
	s_load_dwordx8 s[16:23], s[68:69], 0x1c0
	v_and_b32_e32 v147, 63, v210
	v_lshlrev_b32_e32 v144, 6, v147
	v_lshlrev_b32_e32 v145, 4, v147
	v_mov_b32_e32 v146, 0
	v_lshrrev_b32_e32 v148, 6, v210
	s_lshl_b32 s4, s90, 2
	v_readfirstlane_b32 s5, v148
	s_add_u32 s4, s4, s5
	s_lshl_b32 s5, s33, 2
	s_mov_b32 s9, 0x43600000
	s_waitcnt lgkmcnt(0)
	s_mov_b32 s8, 0
	s_mov_b32 s28, s4
.Lp10_conv_batch:
	s_mov_b32 s6, s28
	s_lshl_b32 s7, s6, 12
	s_add_u32 s24, s12, s7
	s_addc_u32 s25, s13, 0
	global_load_dwordx4 v[0:3], v144, s[24:25]
	global_load_dwordx4 v[4:7], v144, s[24:25] offset:16
	global_load_dwordx4 v[8:11], v144, s[24:25] offset:32
	global_load_dwordx4 v[12:15], v144, s[24:25] offset:48
	s_mul_i32 s6, s5, 1
	s_add_u32 s6, s6, s28
	s_lshl_b32 s7, s6, 12
	s_add_u32 s24, s12, s7
	s_addc_u32 s25, s13, 0
	global_load_dwordx4 v[16:19], v144, s[24:25]
	global_load_dwordx4 v[20:23], v144, s[24:25] offset:16
	global_load_dwordx4 v[24:27], v144, s[24:25] offset:32
	global_load_dwordx4 v[28:31], v144, s[24:25] offset:48
	s_mul_i32 s6, s5, 2
	s_add_u32 s6, s6, s28
	s_lshl_b32 s7, s6, 12
	s_add_u32 s24, s12, s7
	s_addc_u32 s25, s13, 0
	global_load_dwordx4 v[32:35], v144, s[24:25]
	global_load_dwordx4 v[36:39], v144, s[24:25] offset:16
	global_load_dwordx4 v[40:43], v144, s[24:25] offset:32
	global_load_dwordx4 v[44:47], v144, s[24:25] offset:48
	s_mul_i32 s6, s5, 3
	s_add_u32 s6, s6, s28
	s_lshl_b32 s7, s6, 12
	s_add_u32 s24, s12, s7
	s_addc_u32 s25, s13, 0
	global_load_dwordx4 v[48:51], v144, s[24:25]
	global_load_dwordx4 v[52:55], v144, s[24:25] offset:16
	global_load_dwordx4 v[56:59], v144, s[24:25] offset:32
	global_load_dwordx4 v[60:63], v144, s[24:25] offset:48
	s_waitcnt vmcnt(12)
	v_max3_f32 v128, |v0|, |v1|, |v2|
	v_max3_f32 v128, v128, |v3|, |v4|
	v_max3_f32 v128, v128, |v5|, |v6|
	v_max3_f32 v128, v128, |v7|, |v8|
	v_max3_f32 v128, v128, |v9|, |v10|
	v_max3_f32 v128, v128, |v11|, |v12|
	v_max3_f32 v128, v128, |v13|, |v14|
	v_max_f32_e64 v128, v128, |v15|
	s_nop 1
	v_max_f32_dpp v128, v128, v128 row_ror:8 row_mask:0xf bank_mask:0xf
	s_nop 1
	v_max_f32_dpp v128, v128, v128 row_ror:4 row_mask:0xf bank_mask:0xf
	s_nop 1
	v_max_f32_dpp v128, v128, v128 row_ror:2 row_mask:0xf bank_mask:0xf
	s_nop 1
	v_max_f32_dpp v128, v128, v128 row_ror:1 row_mask:0xf bank_mask:0xf
	s_nop 0
	v_readlane_b32 s26, v128, 0
	v_readlane_b32 s27, v128, 16
	v_readlane_b32 s29, v128, 32
	v_readlane_b32 s30, v128, 48
	s_max_u32 s26, s26, s27
	s_max_u32 s29, s29, s30
	s_max_u32 s26, s26, s29
	v_mov_b32_e32 v130, s26
	v_cmp_lt_f32_e64 s[30:31], 0, v130
	v_mul_f32_e32 v131, 0x3b924925, v130
	v_div_scale_f32 v133, s[10:11], v130, v130, s9
	v_rcp_f32_e32 v134, v133
	v_div_scale_f32 v135, vcc, s9, v130, s9
	v_fma_f32 v129, -v133, v134, 1.0
	v_fmac_f32_e32 v134, v129, v134
	v_mul_f32_e32 v129, v135, v134
	v_fma_f32 v132, -v133, v129, v135
	v_fmac_f32_e32 v129, v132, v134
	v_fma_f32 v133, -v133, v129, v135
	v_div_fmas_f32 v133, v133, v134, v129
	v_div_fixup_f32 v132, v133, v130, s9
	v_cndmask_b32_e64 v132, 1.0, v132, s[30:31]
	v_cndmask_b32_e64 v131, 1.0, v131, s[30:31]
	v_mul_f32_e32 v0, v0, v132
	v_mul_f32_e32 v1, v1, v132
	v_mul_f32_e32 v2, v2, v132
	v_mul_f32_e32 v3, v3, v132
	v_mul_f32_e32 v4, v4, v132
	v_mul_f32_e32 v5, v5, v132
	v_mul_f32_e32 v6, v6, v132
	v_mul_f32_e32 v7, v7, v132
	v_mul_f32_e32 v8, v8, v132
	v_mul_f32_e32 v9, v9, v132
	v_mul_f32_e32 v10, v10, v132
	v_mul_f32_e32 v11, v11, v132
	v_mul_f32_e32 v12, v12, v132
	v_mul_f32_e32 v13, v13, v132
	v_mul_f32_e32 v14, v14, v132
	v_mul_f32_e32 v15, v15, v132
	v_mov_b32_e32 v136, 0
	v_mov_b32_e32 v137, 0
	v_mov_b32_e32 v138, 0
	v_mov_b32_e32 v139, 0
	v_cvt_pk_fp8_f32 v136, v0, v1
	v_cvt_pk_fp8_f32 v136, v2, v3 op_sel:[0,0,1]
	v_cvt_pk_fp8_f32 v137, v4, v5
	v_cvt_pk_fp8_f32 v137, v6, v7 op_sel:[0,0,1]
	v_cvt_pk_fp8_f32 v138, v8, v9
	v_cvt_pk_fp8_f32 v138, v10, v11 op_sel:[0,0,1]
	v_cvt_pk_fp8_f32 v139, v12, v13
	v_cvt_pk_fp8_f32 v139, v14, v15 op_sel:[0,0,1]
	s_mov_b32 s6, s28
	s_lshl_b32 s7, s6, 10
	s_add_u32 s24, s16, s7
	s_addc_u32 s25, s17, 0
	global_store_dwordx4 v145, v[136:139], s[24:25]
	s_lshl_b32 s7, s6, 2
	s_add_u32 s24, s20, s7
	s_addc_u32 s25, s21, 0
	s_mov_b64 exec, 1
	global_store_dword v146, v131, s[24:25]
	s_mov_b64 exec, -1
	s_waitcnt vmcnt(10)
; DEVI void conv_fp8_rows(const float* __restrict__ src, unsigned char* __restrict__ dst, float* __restrict__ inv_scale,
;                         int rows, int gw, int nw, int lane) {
;     ...
;     for (int i = 0; i < 4; ++i) { v[0][i] = p0[i]; v[1][i] = p1[i]; }
;     float mx[2];
; #pragma unroll
;     for (int q = 0; q < 2; ++q) {
;       float m = 0.f;
; #pragma unroll
;       for (int i = 0; i < 4; ++i)
;         m = fmaxf(m, fmaxf(fmaxf(fabsf(v[q][i].x), fabsf(v[q][i].y)), fmaxf(fabsf(v[q][i].z), fabsf(v[q][i].w))));
;       mx[q] = m;
;     }
; #pragma unroll
;     for (int o = 32; o; o >>= 1) { mx[0] = fmaxf(mx[0], __shfl_xor(mx[0], o)); mx[1] = fmaxf(mx[1], __shfl_xor(mx[1], o)); }
; #pragma unroll
;     for (int q = 0; q < 2; ++q) {
;       if (q == 1 && !has1) break;
;       const int r = q ? r1 : r0;
;       const float sc = mx[q] > 0.f ? 224.f / mx[q] : 1.f;
;       if (lane == 0) inv_scale[r] = mx[q] > 0.f ? mx[q] * (1.f / 224.f) : 1.f;
;       uint4 o4;
;       o4.x = pk4_fp8(v[q][0].x * sc, v[q][0].y * sc, v[q][0].z * sc, v[q][0].w * sc);
;       o4.y = pk4_fp8(v[q][1].x * sc, v[q][1].y * sc, v[q][1].z * sc, v[q][1].w * sc);
;       o4.z = pk4_fp8(v[q][2].x * sc, v[q][2].y * sc, v[q][2].z * sc, v[q][2].w * sc);
;       o4.w = pk4_fp8(v[q][3].x * sc, v[q][3].y * sc, v[q][3].z * sc, v[q][3].w * sc);
;       ((uint4*)(dst + (size_t)r * 1024))[lane] = o4;
	v_max3_f32 v128, |v16|, |v17|, |v18|
	v_max3_f32 v128, v128, |v19|, |v20|
	v_max3_f32 v128, v128, |v21|, |v22|
	v_max3_f32 v128, v128, |v23|, |v24|
	v_max3_f32 v128, v128, |v25|, |v26|
	v_max3_f32 v128, v128, |v27|, |v28|
	v_max3_f32 v128, v128, |v29|, |v30|
	v_max_f32_e64 v128, v128, |v31|
	s_nop 1
	v_max_f32_dpp v128, v128, v128 row_ror:8 row_mask:0xf bank_mask:0xf
	s_nop 1
	v_max_f32_dpp v128, v128, v128 row_ror:4 row_mask:0xf bank_mask:0xf
	s_nop 1
	v_max_f32_dpp v128, v128, v128 row_ror:2 row_mask:0xf bank_mask:0xf
	s_nop 1
	v_max_f32_dpp v128, v128, v128 row_ror:1 row_mask:0xf bank_mask:0xf
	s_nop 0
	v_readlane_b32 s26, v128, 0
	v_readlane_b32 s27, v128, 16
	v_readlane_b32 s29, v128, 32
	v_readlane_b32 s30, v128, 48
	s_max_u32 s26, s26, s27
	s_max_u32 s29, s29, s30
	s_max_u32 s26, s26, s29
	v_mov_b32_e32 v130, s26
	v_cmp_lt_f32_e64 s[30:31], 0, v130
	v_mul_f32_e32 v131, 0x3b924925, v130
	v_div_scale_f32 v133, s[10:11], v130, v130, s9
	v_rcp_f32_e32 v134, v133
	v_div_scale_f32 v135, vcc, s9, v130, s9
	v_fma_f32 v129, -v133, v134, 1.0
	v_fmac_f32_e32 v134, v129, v134
	v_mul_f32_e32 v129, v135, v134
	v_fma_f32 v132, -v133, v129, v135
	v_fmac_f32_e32 v129, v132, v134
	v_fma_f32 v133, -v133, v129, v135
	v_div_fmas_f32 v133, v133, v134, v129
	v_div_fixup_f32 v132, v133, v130, s9
	v_cndmask_b32_e64 v132, 1.0, v132, s[30:31]
	v_cndmask_b32_e64 v131, 1.0, v131, s[30:31]
	v_mul_f32_e32 v16, v16, v132
	v_mul_f32_e32 v17, v17, v132
	v_mul_f32_e32 v18, v18, v132
	v_mul_f32_e32 v19, v19, v132
	v_mul_f32_e32 v20, v20, v132
	v_mul_f32_e32 v21, v21, v132
	v_mul_f32_e32 v22, v22, v132
	v_mul_f32_e32 v23, v23, v132
	v_mul_f32_e32 v24, v24, v132
	v_mul_f32_e32 v25, v25, v132
	v_mul_f32_e32 v26, v26, v132
	v_mul_f32_e32 v27, v27, v132
	v_mul_f32_e32 v28, v28, v132
	v_mul_f32_e32 v29, v29, v132
	v_mul_f32_e32 v30, v30, v132
	v_mul_f32_e32 v31, v31, v132
	v_mov_b32_e32 v140, 0
	v_mov_b32_e32 v141, 0
	v_mov_b32_e32 v142, 0
	v_mov_b32_e32 v143, 0
	v_cvt_pk_fp8_f32 v140, v16, v17
	v_cvt_pk_fp8_f32 v140, v18, v19 op_sel:[0,0,1]
	v_cvt_pk_fp8_f32 v141, v20, v21
	v_cvt_pk_fp8_f32 v141, v22, v23 op_sel:[0,0,1]
	v_cvt_pk_fp8_f32 v142, v24, v25
	v_cvt_pk_fp8_f32 v142, v26, v27 op_sel:[0,0,1]
	v_cvt_pk_fp8_f32 v143, v28, v29
	v_cvt_pk_fp8_f32 v143, v30, v31 op_sel:[0,0,1]
	s_mul_i32 s6, s5, 1
	s_add_u32 s6, s6, s28
	s_lshl_b32 s7, s6, 10
	s_add_u32 s24, s16, s7
	s_addc_u32 s25, s17, 0
	global_store_dwordx4 v145, v[140:143], s[24:25]
	s_lshl_b32 s7, s6, 2
	s_add_u32 s24, s20, s7
	s_addc_u32 s25, s21, 0
	s_mov_b64 exec, 1
	global_store_dword v146, v131, s[24:25]
	s_mov_b64 exec, -1
	s_waitcnt vmcnt(8)
	v_max3_f32 v128, |v32|, |v33|, |v34|
	v_max3_f32 v128, v128, |v35|, |v36|
	v_max3_f32 v128, v128, |v37|, |v38|
	v_max3_f32 v128, v128, |v39|, |v40|
	v_max3_f32 v128, v128, |v41|, |v42|
	v_max3_f32 v128, v128, |v43|, |v44|
	v_max3_f32 v128, v128, |v45|, |v46|
	v_max_f32_e64 v128, v128, |v47|
	s_nop 1
	v_max_f32_dpp v128, v128, v128 row_ror:8 row_mask:0xf bank_mask:0xf
	s_nop 1
	v_max_f32_dpp v128, v128, v128 row_ror:4 row_mask:0xf bank_mask:0xf
	s_nop 1
	v_max_f32_dpp v128, v128, v128 row_ror:2 row_mask:0xf bank_mask:0xf
	s_nop 1
	v_max_f32_dpp v128, v128, v128 row_ror:1 row_mask:0xf bank_mask:0xf
	s_nop 0
	v_readlane_b32 s26, v128, 0
	v_readlane_b32 s27, v128, 16
	v_readlane_b32 s29, v128, 32
	v_readlane_b32 s30, v128, 48
	s_max_u32 s26, s26, s27
	s_max_u32 s29, s29, s30
	s_max_u32 s26, s26, s29
	v_mov_b32_e32 v130, s26
	v_cmp_lt_f32_e64 s[30:31], 0, v130
	v_mul_f32_e32 v131, 0x3b924925, v130
	v_div_scale_f32 v133, s[10:11], v130, v130, s9
	v_rcp_f32_e32 v134, v133
	v_div_scale_f32 v135, vcc, s9, v130, s9
	v_fma_f32 v129, -v133, v134, 1.0
	v_fmac_f32_e32 v134, v129, v134
	v_mul_f32_e32 v129, v135, v134
	v_fma_f32 v132, -v133, v129, v135
	v_fmac_f32_e32 v129, v132, v134
	v_fma_f32 v133, -v133, v129, v135
	v_div_fmas_f32 v133, v133, v134, v129
	v_div_fixup_f32 v132, v133, v130, s9
	v_cndmask_b32_e64 v132, 1.0, v132, s[30:31]
	v_cndmask_b32_e64 v131, 1.0, v131, s[30:31]
	v_mul_f32_e32 v32, v32, v132
	v_mul_f32_e32 v33, v33, v132
	v_mul_f32_e32 v34, v34, v132
	v_mul_f32_e32 v35, v35, v132
	v_mul_f32_e32 v36, v36, v132
	v_mul_f32_e32 v37, v37, v132
	v_mul_f32_e32 v38, v38, v132
	v_mul_f32_e32 v39, v39, v132
	v_mul_f32_e32 v40, v40, v132
	v_mul_f32_e32 v41, v41, v132
	v_mul_f32_e32 v42, v42, v132
	v_mul_f32_e32 v43, v43, v132
	v_mul_f32_e32 v44, v44, v132
	v_mul_f32_e32 v45, v45, v132
	v_mul_f32_e32 v46, v46, v132
	v_mul_f32_e32 v47, v47, v132
	v_mov_b32_e32 v136, 0
	v_mov_b32_e32 v137, 0
	v_mov_b32_e32 v138, 0
	v_mov_b32_e32 v139, 0
	v_cvt_pk_fp8_f32 v136, v32, v33
	v_cvt_pk_fp8_f32 v136, v34, v35 op_sel:[0,0,1]
	v_cvt_pk_fp8_f32 v137, v36, v37
	v_cvt_pk_fp8_f32 v137, v38, v39 op_sel:[0,0,1]
	v_cvt_pk_fp8_f32 v138, v40, v41
	v_cvt_pk_fp8_f32 v138, v42, v43 op_sel:[0,0,1]
	v_cvt_pk_fp8_f32 v139, v44, v45
	v_cvt_pk_fp8_f32 v139, v46, v47 op_sel:[0,0,1]
	s_mul_i32 s6, s5, 2
	s_add_u32 s6, s6, s28
	s_lshl_b32 s7, s6, 10
	s_add_u32 s24, s16, s7
	s_addc_u32 s25, s17, 0
	global_store_dwordx4 v145, v[136:139], s[24:25]
	s_lshl_b32 s7, s6, 2
	s_add_u32 s24, s20, s7
	s_addc_u32 s25, s21, 0
	s_mov_b64 exec, 1
	global_store_dword v146, v131, s[24:25]
	s_mov_b64 exec, -1
	s_waitcnt vmcnt(6)
; DEVI void conv_fp8_rows(const float* __restrict__ src, unsigned char* __restrict__ dst, float* __restrict__ inv_scale,
;                         int rows, int gw, int nw, int lane) {
;   for (int r0 = gw; r0 < rows; r0 += 2 * nw) {
;     ...
;     for (int i = 0; i < 4; ++i) { v[0][i] = p0[i]; v[1][i] = p1[i]; }
;     float mx[2];
; #pragma unroll
;     for (int q = 0; q < 2; ++q) {
;       float m = 0.f;
; #pragma unroll
;       for (int i = 0; i < 4; ++i)
;         m = fmaxf(m, fmaxf(fmaxf(fabsf(v[q][i].x), fabsf(v[q][i].y)), fmaxf(fabsf(v[q][i].z), fabsf(v[q][i].w))));
;       mx[q] = m;
;     }
; #pragma unroll
;     for (int o = 32; o; o >>= 1) { mx[0] = fmaxf(mx[0], __shfl_xor(mx[0], o)); mx[1] = fmaxf(mx[1], __shfl_xor(mx[1], o)); }
; #pragma unroll
;     for (int q = 0; q < 2; ++q) {
;       if (q == 1 && !has1) break;
;       const int r = q ? r1 : r0;
;       const float sc = mx[q] > 0.f ? 224.f / mx[q] : 1.f;
;       if (lane == 0) inv_scale[r] = mx[q] > 0.f ? mx[q] * (1.f / 224.f) : 1.f;
;       uint4 o4;
;       o4.x = pk4_fp8(v[q][0].x * sc, v[q][0].y * sc, v[q][0].z * sc, v[q][0].w * sc);
;       o4.y = pk4_fp8(v[q][1].x * sc, v[q][1].y * sc, v[q][1].z * sc, v[q][1].w * sc);
;       o4.z = pk4_fp8(v[q][2].x * sc, v[q][2].y * sc, v[q][2].z * sc, v[q][2].w * sc);
;       o4.w = pk4_fp8(v[q][3].x * sc, v[q][3].y * sc, v[q][3].z * sc, v[q][3].w * sc);
;       ((uint4*)(dst + (size_t)r * 1024))[lane] = o4;
;     }
	v_max3_f32 v128, |v48|, |v49|, |v50|
	v_max3_f32 v128, v128, |v51|, |v52|
	v_max3_f32 v128, v128, |v53|, |v54|
	v_max3_f32 v128, v128, |v55|, |v56|
	v_max3_f32 v128, v128, |v57|, |v58|
	v_max3_f32 v128, v128, |v59|, |v60|
	v_max3_f32 v128, v128, |v61|, |v62|
	v_max_f32_e64 v128, v128, |v63|
	s_nop 1
	v_max_f32_dpp v128, v128, v128 row_ror:8 row_mask:0xf bank_mask:0xf
	s_nop 1
	v_max_f32_dpp v128, v128, v128 row_ror:4 row_mask:0xf bank_mask:0xf
	s_nop 1
	v_max_f32_dpp v128, v128, v128 row_ror:2 row_mask:0xf bank_mask:0xf
	s_nop 1
	v_max_f32_dpp v128, v128, v128 row_ror:1 row_mask:0xf bank_mask:0xf
	s_nop 0
	v_readlane_b32 s26, v128, 0
	v_readlane_b32 s27, v128, 16
	v_readlane_b32 s29, v128, 32
	v_readlane_b32 s30, v128, 48
	s_max_u32 s26, s26, s27
	s_max_u32 s29, s29, s30
	s_max_u32 s26, s26, s29
	v_mov_b32_e32 v130, s26
	v_cmp_lt_f32_e64 s[30:31], 0, v130
	v_mul_f32_e32 v131, 0x3b924925, v130
	v_div_scale_f32 v133, s[10:11], v130, v130, s9
	v_rcp_f32_e32 v134, v133
	v_div_scale_f32 v135, vcc, s9, v130, s9
	v_fma_f32 v129, -v133, v134, 1.0
	v_fmac_f32_e32 v134, v129, v134
	v_mul_f32_e32 v129, v135, v134
	v_fma_f32 v132, -v133, v129, v135
	v_fmac_f32_e32 v129, v132, v134
	v_fma_f32 v133, -v133, v129, v135
	v_div_fmas_f32 v133, v133, v134, v129
	v_div_fixup_f32 v132, v133, v130, s9
	v_cndmask_b32_e64 v132, 1.0, v132, s[30:31]
	v_cndmask_b32_e64 v131, 1.0, v131, s[30:31]
	v_mul_f32_e32 v48, v48, v132
	v_mul_f32_e32 v49, v49, v132
	v_mul_f32_e32 v50, v50, v132
	v_mul_f32_e32 v51, v51, v132
	v_mul_f32_e32 v52, v52, v132
	v_mul_f32_e32 v53, v53, v132
	v_mul_f32_e32 v54, v54, v132
	v_mul_f32_e32 v55, v55, v132
	v_mul_f32_e32 v56, v56, v132
	v_mul_f32_e32 v57, v57, v132
	v_mul_f32_e32 v58, v58, v132
	v_mul_f32_e32 v59, v59, v132
	v_mul_f32_e32 v60, v60, v132
	v_mul_f32_e32 v61, v61, v132
	v_mul_f32_e32 v62, v62, v132
	v_mul_f32_e32 v63, v63, v132
	v_mov_b32_e32 v140, 0
	v_mov_b32_e32 v141, 0
	v_mov_b32_e32 v142, 0
	v_mov_b32_e32 v143, 0
	v_cvt_pk_fp8_f32 v140, v48, v49
	v_cvt_pk_fp8_f32 v140, v50, v51 op_sel:[0,0,1]
	v_cvt_pk_fp8_f32 v141, v52, v53
	v_cvt_pk_fp8_f32 v141, v54, v55 op_sel:[0,0,1]
	v_cvt_pk_fp8_f32 v142, v56, v57
	v_cvt_pk_fp8_f32 v142, v58, v59 op_sel:[0,0,1]
	v_cvt_pk_fp8_f32 v143, v60, v61
	v_cvt_pk_fp8_f32 v143, v62, v63 op_sel:[0,0,1]
	s_mul_i32 s6, s5, 3
	s_add_u32 s6, s6, s28
	s_lshl_b32 s7, s6, 10
	s_add_u32 s24, s16, s7
	s_addc_u32 s25, s17, 0
	global_store_dwordx4 v145, v[140:143], s[24:25]
	s_lshl_b32 s7, s6, 2
	s_add_u32 s24, s20, s7
	s_addc_u32 s25, s21, 0
	s_mov_b64 exec, 1
	global_store_dword v146, v131, s[24:25]
	s_mov_b64 exec, -1
	s_lshl_b32 s6, s5, 2
	s_add_u32 s28, s28, s6
	s_add_u32 s8, s8, 1
	s_cmp_lg_u32 s8, 2
	s_cbranch_scc1 .Lp10_conv_same
	s_mov_b64 s[12:13], s[14:15]
	s_mov_b64 s[16:17], s[18:19]
	s_mov_b64 s[20:21], s[22:23]
	s_mov_b32 s28, s4
.Lp10_conv_same:
	s_cmp_lt_u32 s8, 4
	s_cbranch_scc1 .Lp10_conv_batch
	s_mov_b64 s[10:11], 0
	s_branch .LBB0_1239
